# v65 + non-temporal hint on the PLE tile stores (consumed ~300 us later; keeps weights resident)
# speedup vs baseline: 1.0184x; 1.0152x over previous
; __device__ __forceinline__ u32x4 pack8(f32x4 a, f32x4 b) { u32x4 w; w.x = cvt_pk_bf16(a[0], a[1]); w.y = cvt_pk_bf16(a[2], a[3]); w.z = cvt_pk_bf16(b[0], b[1]); w.w = cvt_pk_bf16(b[2], b[3]); return w; }
; #define PG8_BAR __builtin_amdgcn_s_barrier()
; #define EPI_OPAQUE asm volatile("" : "+v"(fr), "+v"(fq));
; template <class Epi, class Order = StaticOrder, bool HALFN = false>
; __device__ __forceinline__ void gemm_phase(LAS unsigned char* lds, const Gemm g, const Epi& E) {
;     ...
;         if (wr == 0) PG8_BAR;
;         E(acc, cur, wr, wc, fr, fq);
;         if (!has_next) break;
;         if constexpr (Epi::INIT) E.init(acc, nxt, wr, wc, fr, fq);
;         else {
; #pragma unroll
;         for (int a = 0; a < 2; ++a)
; #pragma unroll
;             for (int b = 0; b < 2; ++b)
; #pragma unroll
;                 for (int m = 0; m < 4; ++m)
; #pragma unroll
;                     for (int n = 0; n < 2; ++n) acc[a][b][m][n] = (f32x4){0.f, 0.f, 0.f, 0.f};
;         }
;         cur = nxt; cA = nA; cB = nB; ++ui;
;         if (wr == 1) PG8_BAR;
;     __device__ __forceinline__ void operator()(f32x4 (&acc)[2][2][4][2], const Unit& u, int wr, int wc, int fr, int fq) const {
;         EPI_OPAQUE
;         EPI_ROWS_BEGIN EPI_COLS_BEGIN
;             *(u32x4*)(O + (size_t)row * ldo + col) = pack8(acc[ai][bj][m][0], acc[ai][bj][m][1]);
;         EPI_END EPI_END
;     }
.LBB0_524:
	s_lshl_b32 s4, s56, 8
	v_mov_b32_e32 v141, v1
	v_mov_b32_e32 v143, v138
	s_add_i32 s4, s4, s24
	v_cvt_pk_bf16_f32 v70, v70, v71
	v_add_u32_e32 v142, s4, v141
	s_lshl_b32 s4, s46, 8
	s_or_b32 s4, s4, s25
	v_cvt_pk_bf16_f32 v71, v72, v73
	v_cvt_pk_bf16_f32 v72, v66, v67
	v_add_u32_e32 v66, 0x80, v142
	v_lshl_add_u32 v144, v143, 3, s4
	v_ashrrev_i32_e32 v143, 31, v142
	v_ashrrev_i32_e32 v67, 31, v66
	v_cvt_pk_bf16_f32 v126, v126, v127
	v_cvt_pk_bf16_f32 v127, v128, v129
	v_cvt_pk_bf16_f32 v128, v122, v123
	v_lshlrev_b64 v[122:123], 12, v[142:143]
	v_ashrrev_i32_e32 v145, 31, v144
	v_cvt_pk_bf16_f32 v62, v62, v63
	v_cvt_pk_bf16_f32 v63, v64, v65
	v_cvt_pk_bf16_f32 v64, v58, v59
	v_lshlrev_b64 v[58:59], 12, v[66:67]
	v_cvt_pk_bf16_f32 v129, v124, v125
	v_lshl_add_u64 v[122:123], s[44:45], 0, v[122:123]
	s_lshl_b32 s98, s46, 13
	s_lshl_b32 s99, s25, 6
	s_add_i32 s98, s98, s99
	s_movk_i32 s99, 0xf010
	v_lshl_add_u32 v124, v138, 8, s98
	v_mad_i32_i24 v124, v1, s99, v124
	v_ashrrev_i32_e32 v125, 31, v124
	v_lshl_add_u64 v[58:59], s[44:45], 0, v[58:59]
	v_lshl_add_u64 v[122:123], v[122:123], 0, v[124:125]
	v_cvt_pk_bf16_f32 v110, v110, v111
	v_cvt_pk_bf16_f32 v111, v112, v113
	v_cvt_pk_bf16_f32 v112, v106, v107
	v_cvt_pk_bf16_f32 v113, v108, v109
	v_lshl_add_u64 v[58:59], v[58:59], 0, v[124:125]
	v_cvt_pk_bf16_f32 v46, v46, v47
	v_cvt_pk_bf16_f32 v47, v48, v49
	v_cvt_pk_bf16_f32 v48, v42, v43
	v_cvt_pk_bf16_f32 v49, v44, v45
	global_store_dwordx4 v[122:123], v[110:113], off offset:1024 nt
	global_store_dwordx4 v[58:59], v[46:49], off offset:1024 nt
	v_cvt_pk_bf16_f32 v94, v94, v95
	v_add_u32_e32 v110, 16, v142
	v_add_u32_e32 v46, 0x90, v142
	v_ashrrev_i32_e32 v111, 31, v110
	v_ashrrev_i32_e32 v47, 31, v46
	v_lshlrev_b64 v[110:111], 12, v[110:111]
	v_lshlrev_b64 v[46:47], 12, v[46:47]
	v_lshl_add_u64 v[110:111], s[44:45], 0, v[110:111]
	v_lshl_add_u64 v[46:47], s[44:45], 0, v[46:47]
	v_lshl_add_u64 v[110:111], v[110:111], 0, v[124:125]
	v_cvt_pk_bf16_f32 v95, v96, v97
	v_cvt_pk_bf16_f32 v96, v90, v91
	v_cvt_pk_bf16_f32 v97, v92, v93
	v_lshl_add_u64 v[46:47], v[46:47], 0, v[124:125]
	v_cvt_pk_bf16_f32 v30, v30, v31
	v_cvt_pk_bf16_f32 v31, v32, v33
	v_cvt_pk_bf16_f32 v32, v26, v27
	v_cvt_pk_bf16_f32 v33, v28, v29
	global_store_dwordx4 v[110:111], v[94:97], off offset:1024 nt
	global_store_dwordx4 v[46:47], v[30:33], off offset:1024 nt
	v_cvt_pk_bf16_f32 v78, v78, v79
	v_add_u32_e32 v94, 32, v142
	v_add_u32_e32 v30, 0xa0, v142
	v_ashrrev_i32_e32 v95, 31, v94
	v_ashrrev_i32_e32 v31, 31, v30
	v_lshlrev_b64 v[94:95], 12, v[94:95]
	v_lshlrev_b64 v[30:31], 12, v[30:31]
	v_lshl_add_u64 v[94:95], s[44:45], 0, v[94:95]
	v_lshl_add_u64 v[30:31], s[44:45], 0, v[30:31]
	v_lshl_add_u64 v[94:95], v[94:95], 0, v[124:125]
	v_cvt_pk_bf16_f32 v79, v80, v81
	v_cvt_pk_bf16_f32 v80, v74, v75
	v_cvt_pk_bf16_f32 v81, v76, v77
	v_lshl_add_u64 v[30:31], v[30:31], 0, v[124:125]
	v_cvt_pk_bf16_f32 v14, v14, v15
	v_cvt_pk_bf16_f32 v15, v16, v17
	v_cvt_pk_bf16_f32 v16, v10, v11
	v_cvt_pk_bf16_f32 v17, v12, v13
	global_store_dwordx4 v[94:95], v[78:81], off offset:1024 nt
	global_store_dwordx4 v[30:31], v[14:17], off offset:1024 nt
	v_cvt_pk_bf16_f32 v106, v118, v119
	v_add_u32_e32 v78, 48, v142
	v_add_u32_e32 v14, 0xb0, v142
	v_ashrrev_i32_e32 v79, 31, v78
	v_ashrrev_i32_e32 v15, 31, v14
	v_lshlrev_b64 v[78:79], 12, v[78:79]
	v_lshlrev_b64 v[14:15], 12, v[14:15]
	v_lshl_add_u64 v[78:79], s[44:45], 0, v[78:79]
	v_lshl_add_u64 v[14:15], s[44:45], 0, v[14:15]
	v_cvt_pk_bf16_f32 v107, v120, v121
	v_cvt_pk_bf16_f32 v108, v114, v115
	v_cvt_pk_bf16_f32 v109, v116, v117
	v_cvt_pk_bf16_f32 v90, v102, v103
	v_cvt_pk_bf16_f32 v91, v104, v105
	v_cvt_pk_bf16_f32 v92, v98, v99
	v_cvt_pk_bf16_f32 v93, v100, v101
	v_cvt_pk_bf16_f32 v74, v86, v87
	v_cvt_pk_bf16_f32 v75, v88, v89
	v_cvt_pk_bf16_f32 v76, v82, v83
	v_cvt_pk_bf16_f32 v77, v84, v85
	v_lshl_add_u64 v[78:79], v[78:79], 0, v[124:125]
	v_cvt_pk_bf16_f32 v73, v68, v69
	v_cvt_pk_bf16_f32 v65, v60, v61
	v_cvt_pk_bf16_f32 v42, v54, v55
	v_cvt_pk_bf16_f32 v43, v56, v57
	v_cvt_pk_bf16_f32 v44, v50, v51
	v_cvt_pk_bf16_f32 v45, v52, v53
	v_cvt_pk_bf16_f32 v26, v38, v39
	v_cvt_pk_bf16_f32 v27, v40, v41
	v_cvt_pk_bf16_f32 v28, v34, v35
	v_cvt_pk_bf16_f32 v29, v36, v37
	v_cvt_pk_bf16_f32 v10, v22, v23
	v_cvt_pk_bf16_f32 v11, v24, v25
	v_cvt_pk_bf16_f32 v12, v18, v19
	v_cvt_pk_bf16_f32 v13, v20, v21
	v_lshl_add_u64 v[14:15], v[14:15], 0, v[124:125]
	v_cvt_pk_bf16_f32 v6, v6, v7
	v_cvt_pk_bf16_f32 v7, v8, v9
	v_cvt_pk_bf16_f32 v8, v2, v3
	v_cvt_pk_bf16_f32 v9, v4, v5
	s_andn2_b64 vcc, exec, s[80:81]
	s_mov_b64 s[4:5], -1
	global_store_dwordx4 v[122:123], v[126:129], off nt
	global_store_dwordx4 v[110:111], v[106:109], off nt
	global_store_dwordx4 v[94:95], v[90:93], off nt
	global_store_dwordx4 v[78:79], v[74:77], off nt
	global_store_dwordx4 v[78:79], v[70:73], off offset:1024 nt
	global_store_dwordx4 v[58:59], v[62:65], off nt
	global_store_dwordx4 v[46:47], v[42:45], off nt
	global_store_dwordx4 v[30:31], v[26:29], off nt
	global_store_dwordx4 v[14:15], v[10:13], off nt
	global_store_dwordx4 v[14:15], v[6:9], off offset:1024 nt
	s_cbranch_vccnz .LBB0_506
	s_andn2_b64 vcc, exec, s[40:41]
	s_cbranch_vccnz .LBB0_505
	s_barrier
	s_branch .LBB0_505
